# in-proj K-loop: per-phase s_setprio toggles removed, one static s_setprio 1 for the leading wave group (wr=0)
# baseline (speedup 1.0000x reference)
.LBB0_229:
	s_cmp_ge_i32 s3, s72
	s_cselect_b64 s[0:1], -1, 0
	s_cmp_lt_i32 s3, s73
	s_cselect_b64 s[4:5], -1, 0
	s_and_b64 s[0:1], s[0:1], s[4:5]
	v_writelane_b32 v255, s3, 29
	s_andn2_b64 vcc, exec, s[0:1]
	s_cbranch_vccnz .LBB0_299
	s_movk_i32 s0, 0x400
	v_mov_b32_e32 v1, v0
	v_readlane_b32 s1, v252, 8
	v_mbcnt_lo_u32_b32 v1, -1, v1
	v_mbcnt_hi_u32_b32 v1, -1, v1
	v_readlane_b32 s4, v252, 17
	s_waitcnt vmcnt(0)
	v_add_u32_e32 v8, s1, v1
	v_readlane_b32 s5, v252, 18
	s_andn2_b64 vcc, exec, s[4:5]
	v_readfirstlane_b32 s3, v8
	s_cbranch_vccnz .LBB0_248
	s_bitcmp1_b32 s3, 8
	s_cbranch_scc1 .Lprio_skip0
	s_setprio 1
